# P5 in-loop residual prefetch block moved from the trip top to after the first barrier of the trip (next counted vmcnt wait a quarter trip later)
# baseline (speedup 1.0000x reference)
; __device__ __forceinline__ f32x4 bf4_to_f32(u32x2 w) { f32x4 r; r[0] = __uint_as_float(w.x << 16); r[1] = __uint_as_float(w.x & 0xffff0000u); r[2] = __uint_as_float(w.y << 16); r[3] = __uint_as_float(w.y & 0xffff0000u); return r; }
;     __device__ __forceinline__ void fused(f32x4 (&acc)[2][2][4][2], const Unit& u, int wr, int wc, int fr, int fq, PG8_LAS unsigned char* lds, int wid, int lane) const {
;     ...
;             for (int m = 0; m < 4; ++m) { const int r = ai * HALF + wr * 64 + m * 16 + fr; const size_t off = (size_t)(u.pm * BM + r) * 2048 + col0; float s = 0.f;
;                 const float rr = __builtin_amdgcn_rcpf(r2[ai * 4 + m] * (1.0f / 2048.0f) + 1e-5f);
; #pragma unroll
;                 for (int bj = 0; bj < 2; ++bj)
; #pragma unroll
;                     for (int n = 0; n < 2; ++n) { const f32x4 bs = bf4_to_f32(*(const u32x2*)(base + off + bj * HALF + n * 16)); const f32x4 o = bs + acc[ai][bj][m][n] * rr; acc[ai][bj][m][n] = o;
.LBB0_1031:
	ds_read_b128 v[144:147], v139
	ds_read_b128 v[148:151], v139 offset:1024
	ds_read_b128 v[152:155], v139 offset:2048
	ds_read_b128 v[156:159], v139 offset:3072
	ds_read_b128 v[164:167], v140
	ds_read_b128 v[168:171], v140 offset:1024
	ds_read_b128 v[172:175], v140 offset:2048
	ds_read_b128 v[176:179], v140 offset:3072
	s_add_u32 s12, s8, s10
	s_addc_u32 s13, s9, s11
	s_add_u32 s12, s12, 0x2000100
	s_addc_u32 s13, s13, 0
	s_add_u32 s42, s27, s10
	s_addc_u32 s43, s28, s11
	s_cmpk_eq_i32 s10, 0x3f00
	s_cselect_b32 s15, s3, s13
	s_cselect_b32 s14, s2, s12
	s_cselect_b32 s13, s1, s43
	s_cselect_b32 s12, s0, s42
	s_mov_b32 m0, s30
	v_lshl_add_u64 v[160:161], v[134:135], 0, s[10:11]
	ds_read_b128 v[180:183], v141
	ds_read_b128 v[184:187], v141 offset:1024
	ds_read_b128 v[188:191], v141 offset:2048
	ds_read_b128 v[196:199], v141 offset:3072
	ds_read_b128 v[200:203], v141 offset:4096
	ds_read_b128 v[204:207], v141 offset:5120
	ds_read_b128 v[208:211], v141 offset:6144
	ds_read_b128 v[212:215], v141 offset:7168
	global_load_lds_dwordx4 v[160:161], off
	v_lshl_add_u64 v[160:161], v[136:137], 0, s[10:11]
	s_mov_b32 m0, s31
	s_nop 0
	global_load_lds_dwordx4 v[160:161], off
	s_waitcnt vmcnt(8) lgkmcnt(0)
	s_barrier
	s_cmpk_eq_i32 s29, 118
	s_cbranch_scc0 .Lp5pf_skip
	s_lshl_b32 s46, s64, 8
	s_lshl_b32 s47, s18, 5
	s_lshl_b32 s48, s16, 8
	s_or_b32 s48, s48, s47
	v_add_u32_e32 v216, s46, v162
	v_ashrrev_i32_e32 v217, 31, v216
	v_lshlrev_b64 v[216:217], 12, v[216:217]
	v_lshl_add_u64 v[216:217], s[70:71], 0, v[216:217]
	v_and_or_b32 v192, v138, 12, s48
	v_lshlrev_b32_e32 v192, 1, v192
	v_mov_b32_e32 v193, 0
	v_lshl_add_u64 v[216:217], v[216:217], 0, v[192:193]
	s_mov_b64 s[46:47], 0x10000
	v_lshl_add_u64 v[192:193], v[216:217], 0, s[46:47]
	global_load_dwordx2 v[218:219], v[192:193], off
	global_load_dwordx2 v[220:221], v[192:193], off offset:32
	global_load_dwordx2 v[222:223], v[192:193], off offset:256
	global_load_dwordx2 v[224:225], v[192:193], off offset:288
	s_mov_b64 s[46:47], 0x20000
	v_lshl_add_u64 v[192:193], v[216:217], 0, s[46:47]
	global_load_dwordx2 v[226:227], v[192:193], off
	global_load_dwordx2 v[228:229], v[192:193], off offset:32
	global_load_dwordx2 v[230:231], v[192:193], off offset:256
	global_load_dwordx2 v[232:233], v[192:193], off offset:288
	s_mov_b64 s[46:47], 0x30000
	v_lshl_add_u64 v[192:193], v[216:217], 0, s[46:47]
	global_load_dwordx2 v[234:235], v[192:193], off
	global_load_dwordx2 v[236:237], v[192:193], off offset:32
	global_load_dwordx2 v[238:239], v[192:193], off offset:256
	global_load_dwordx2 v[240:241], v[192:193], off offset:288
	s_mov_b64 s[46:47], 0x80000
	v_lshl_add_u64 v[192:193], v[216:217], 0, s[46:47]
	global_load_dwordx2 v[244:245], v[192:193], off
	global_load_dwordx2 v[246:247], v[192:193], off offset:32
	global_load_dwordx2 v[248:249], v[192:193], off offset:256
	global_load_dwordx2 v[250:251], v[192:193], off offset:288
	s_mov_b64 s[46:47], 0x90000
	v_lshl_add_u64 v[192:193], v[216:217], 0, s[46:47]
	global_load_dwordx2 v[252:253], v[192:193], off
	global_load_dwordx2 v[254:255], v[192:193], off offset:32
	global_load_dwordx2 v[216:217], v[192:193], off offset:256
	s_nop 0
	global_load_dwordx2 v[192:193], v[192:193], off offset:288
.Lp5pf_skip:
	v_mfma_f32_16x16x32_bf16 v[126:129], v[144:147], v[180:183], v[126:129]
	v_mfma_f32_16x16x32_bf16 v[122:125], v[152:155], v[180:183], v[122:125]
	v_mfma_f32_16x16x32_bf16 v[110:113], v[144:147], v[188:191], v[110:113]
	v_mfma_f32_16x16x32_bf16 v[106:109], v[152:155], v[188:191], v[106:109]
	v_mfma_f32_16x16x32_bf16 v[94:97], v[144:147], v[200:203], v[94:97]
	v_mfma_f32_16x16x32_bf16 v[90:93], v[152:155], v[200:203], v[90:93]
	v_mfma_f32_16x16x32_bf16 v[78:81], v[144:147], v[208:211], v[78:81]
	v_mfma_f32_16x16x32_bf16 v[74:77], v[152:155], v[208:211], v[74:77]
	v_mfma_f32_16x16x32_bf16 v[126:129], v[148:151], v[184:187], v[126:129]
	v_mfma_f32_16x16x32_bf16 v[122:125], v[156:159], v[184:187], v[122:125]
	v_mfma_f32_16x16x32_bf16 v[110:113], v[148:151], v[196:199], v[110:113]
	v_mfma_f32_16x16x32_bf16 v[106:109], v[156:159], v[196:199], v[106:109]
	v_mfma_f32_16x16x32_bf16 v[94:97], v[148:151], v[204:207], v[94:97]
	v_mfma_f32_16x16x32_bf16 v[90:93], v[156:159], v[204:207], v[90:93]
	v_mfma_f32_16x16x32_bf16 v[78:81], v[148:151], v[212:215], v[78:81]
	v_mfma_f32_16x16x32_bf16 v[74:77], v[156:159], v[212:215], v[74:77]
	v_mfma_f32_16x16x32_bf16 v[118:121], v[164:167], v[180:183], v[118:121]
	v_mfma_f32_16x16x32_bf16 v[114:117], v[172:175], v[180:183], v[114:117]
	v_mfma_f32_16x16x32_bf16 v[102:105], v[164:167], v[188:191], v[102:105]
	v_mfma_f32_16x16x32_bf16 v[98:101], v[172:175], v[188:191], v[98:101]
	v_mfma_f32_16x16x32_bf16 v[86:89], v[164:167], v[200:203], v[86:89]
	v_mfma_f32_16x16x32_bf16 v[82:85], v[172:175], v[200:203], v[82:85]
	v_mfma_f32_16x16x32_bf16 v[70:73], v[164:167], v[208:211], v[70:73]
	v_mfma_f32_16x16x32_bf16 v[66:69], v[172:175], v[208:211], v[66:69]
	v_mfma_f32_16x16x32_bf16 v[118:121], v[168:171], v[184:187], v[118:121]
	v_mfma_f32_16x16x32_bf16 v[114:117], v[176:179], v[184:187], v[114:117]
	v_mfma_f32_16x16x32_bf16 v[102:105], v[168:171], v[196:199], v[102:105]
	v_mfma_f32_16x16x32_bf16 v[98:101], v[176:179], v[196:199], v[98:101]
	v_mfma_f32_16x16x32_bf16 v[86:89], v[168:171], v[204:207], v[86:89]
	v_mfma_f32_16x16x32_bf16 v[82:85], v[176:179], v[204:207], v[82:85]
	v_mfma_f32_16x16x32_bf16 v[70:73], v[168:171], v[212:215], v[70:73]
	v_mfma_f32_16x16x32_bf16 v[66:69], v[176:179], v[212:215], v[66:69]
	s_barrier
	s_mov_b32 m0, s34
	s_add_u32 s42, s12, 0x200000
	s_addc_u32 s43, s13, 0
	ds_read_b128 v[180:183], v141 offset:16384
	ds_read_b128 v[184:187], v141 offset:17408
	ds_read_b128 v[188:191], v141 offset:18432
	ds_read_b128 v[196:199], v141 offset:19456
	ds_read_b128 v[200:203], v141 offset:20480
	ds_read_b128 v[204:207], v141 offset:21504
	ds_read_b128 v[208:211], v141 offset:22528
	ds_read_b128 v[212:215], v141 offset:23552
	global_load_lds_dwordx4 v130, s[12:13]
	s_mov_b32 m0, s35
	s_nop 0
	global_load_lds_dwordx4 v132, s[12:13]
	s_mov_b32 m0, s36
	s_nop 0
	global_load_lds_dwordx4 v130, s[42:43]
	s_mov_b32 m0, s37
	s_nop 0
	global_load_lds_dwordx4 v132, s[42:43]
	s_mov_b32 m0, s20
	s_nop 0
	global_load_lds_dwordx4 v130, s[14:15]
	s_mov_b32 m0, s21
	s_nop 0
	global_load_lds_dwordx4 v132, s[14:15]
	s_waitcnt vmcnt(8) lgkmcnt(0)
	s_barrier
	v_mfma_f32_16x16x32_bf16 v[62:65], v[144:147], v[180:183], v[62:65]
	v_mfma_f32_16x16x32_bf16 v[58:61], v[152:155], v[180:183], v[58:61]
	v_mfma_f32_16x16x32_bf16 v[46:49], v[144:147], v[188:191], v[46:49]
	v_mfma_f32_16x16x32_bf16 v[42:45], v[152:155], v[188:191], v[42:45]
	v_mfma_f32_16x16x32_bf16 v[30:33], v[144:147], v[200:203], v[30:33]
	v_mfma_f32_16x16x32_bf16 v[26:29], v[152:155], v[200:203], v[26:29]
	v_mfma_f32_16x16x32_bf16 v[14:17], v[144:147], v[208:211], v[14:17]
	v_mfma_f32_16x16x32_bf16 v[10:13], v[152:155], v[208:211], v[10:13]
	v_mfma_f32_16x16x32_bf16 v[62:65], v[148:151], v[184:187], v[62:65]
	v_mfma_f32_16x16x32_bf16 v[58:61], v[156:159], v[184:187], v[58:61]
	v_mfma_f32_16x16x32_bf16 v[46:49], v[148:151], v[196:199], v[46:49]
	v_mfma_f32_16x16x32_bf16 v[42:45], v[156:159], v[196:199], v[42:45]
	v_mfma_f32_16x16x32_bf16 v[30:33], v[148:151], v[204:207], v[30:33]
	v_mfma_f32_16x16x32_bf16 v[26:29], v[156:159], v[204:207], v[26:29]
	v_mfma_f32_16x16x32_bf16 v[14:17], v[148:151], v[212:215], v[14:17]
	v_mfma_f32_16x16x32_bf16 v[10:13], v[156:159], v[212:215], v[10:13]
	v_mfma_f32_16x16x32_bf16 v[54:57], v[164:167], v[180:183], v[54:57]
	v_mfma_f32_16x16x32_bf16 v[50:53], v[172:175], v[180:183], v[50:53]
	v_mfma_f32_16x16x32_bf16 v[38:41], v[164:167], v[188:191], v[38:41]
	v_mfma_f32_16x16x32_bf16 v[34:37], v[172:175], v[188:191], v[34:37]
	v_mfma_f32_16x16x32_bf16 v[22:25], v[164:167], v[200:203], v[22:25]
	v_mfma_f32_16x16x32_bf16 v[18:21], v[172:175], v[200:203], v[18:21]
	v_mfma_f32_16x16x32_bf16 v[6:9], v[164:167], v[208:211], v[6:9]
	v_mfma_f32_16x16x32_bf16 v[2:5], v[172:175], v[208:211], v[2:5]
	v_mfma_f32_16x16x32_bf16 v[54:57], v[168:171], v[184:187], v[54:57]
	v_mfma_f32_16x16x32_bf16 v[50:53], v[176:179], v[184:187], v[50:53]
	v_mfma_f32_16x16x32_bf16 v[38:41], v[168:171], v[196:199], v[38:41]
	v_mfma_f32_16x16x32_bf16 v[34:37], v[176:179], v[196:199], v[34:37]
	v_mfma_f32_16x16x32_bf16 v[22:25], v[168:171], v[204:207], v[22:25]
	v_mfma_f32_16x16x32_bf16 v[18:21], v[176:179], v[204:207], v[18:21]
	v_mfma_f32_16x16x32_bf16 v[6:9], v[168:171], v[212:215], v[6:9]
	v_mfma_f32_16x16x32_bf16 v[2:5], v[176:179], v[212:215], v[2:5]
	s_barrier
	ds_read_b128 v[144:147], v142
	ds_read_b128 v[148:151], v142 offset:1024
	ds_read_b128 v[152:155], v142 offset:2048
	ds_read_b128 v[156:159], v142 offset:3072
	ds_read_b128 v[164:167], v143
	ds_read_b128 v[168:171], v143 offset:1024
	ds_read_b128 v[172:175], v143 offset:2048
	ds_read_b128 v[176:179], v143 offset:3072
	s_add_u32 s14, s14, 0x200000
	s_addc_u32 s15, s15, 0
	s_mov_b32 m0, s22
	ds_read_b128 v[180:183], v141 offset:32768
	ds_read_b128 v[184:187], v141 offset:33792
	ds_read_b128 v[188:191], v141 offset:34816
	ds_read_b128 v[196:199], v141 offset:35840
	ds_read_b128 v[200:203], v141 offset:36864
	ds_read_b128 v[204:207], v141 offset:37888
	ds_read_b128 v[208:211], v141 offset:38912
	ds_read_b128 v[212:215], v141 offset:39936
	global_load_lds_dwordx4 v130, s[14:15]
	s_mov_b32 m0, s23
	s_nop 0
	global_load_lds_dwordx4 v132, s[14:15]
	s_waitcnt vmcnt(8) lgkmcnt(0)
	s_barrier
	v_mfma_f32_16x16x32_bf16 v[126:129], v[144:147], v[180:183], v[126:129]
	v_mfma_f32_16x16x32_bf16 v[122:125], v[152:155], v[180:183], v[122:125]
	v_mfma_f32_16x16x32_bf16 v[110:113], v[144:147], v[188:191], v[110:113]
	v_mfma_f32_16x16x32_bf16 v[106:109], v[152:155], v[188:191], v[106:109]
	v_mfma_f32_16x16x32_bf16 v[94:97], v[144:147], v[200:203], v[94:97]
	v_mfma_f32_16x16x32_bf16 v[90:93], v[152:155], v[200:203], v[90:93]
	v_mfma_f32_16x16x32_bf16 v[78:81], v[144:147], v[208:211], v[78:81]
	v_mfma_f32_16x16x32_bf16 v[74:77], v[152:155], v[208:211], v[74:77]
	v_mfma_f32_16x16x32_bf16 v[126:129], v[148:151], v[184:187], v[126:129]
	v_mfma_f32_16x16x32_bf16 v[122:125], v[156:159], v[184:187], v[122:125]
	v_mfma_f32_16x16x32_bf16 v[110:113], v[148:151], v[196:199], v[110:113]
	v_mfma_f32_16x16x32_bf16 v[106:109], v[156:159], v[196:199], v[106:109]
	v_mfma_f32_16x16x32_bf16 v[94:97], v[148:151], v[204:207], v[94:97]
	v_mfma_f32_16x16x32_bf16 v[90:93], v[156:159], v[204:207], v[90:93]
	v_mfma_f32_16x16x32_bf16 v[78:81], v[148:151], v[212:215], v[78:81]
	v_mfma_f32_16x16x32_bf16 v[74:77], v[156:159], v[212:215], v[74:77]
	v_mfma_f32_16x16x32_bf16 v[118:121], v[164:167], v[180:183], v[118:121]
	v_mfma_f32_16x16x32_bf16 v[114:117], v[172:175], v[180:183], v[114:117]
	v_mfma_f32_16x16x32_bf16 v[102:105], v[164:167], v[188:191], v[102:105]
	v_mfma_f32_16x16x32_bf16 v[98:101], v[172:175], v[188:191], v[98:101]
	v_mfma_f32_16x16x32_bf16 v[86:89], v[164:167], v[200:203], v[86:89]
	v_mfma_f32_16x16x32_bf16 v[82:85], v[172:175], v[200:203], v[82:85]
	v_mfma_f32_16x16x32_bf16 v[70:73], v[164:167], v[208:211], v[70:73]
	v_mfma_f32_16x16x32_bf16 v[66:69], v[172:175], v[208:211], v[66:69]
	v_mfma_f32_16x16x32_bf16 v[118:121], v[168:171], v[184:187], v[118:121]
	v_mfma_f32_16x16x32_bf16 v[114:117], v[176:179], v[184:187], v[114:117]
	v_mfma_f32_16x16x32_bf16 v[102:105], v[168:171], v[196:199], v[102:105]
	v_mfma_f32_16x16x32_bf16 v[98:101], v[176:179], v[196:199], v[98:101]
	v_mfma_f32_16x16x32_bf16 v[86:89], v[168:171], v[204:207], v[86:89]
	v_mfma_f32_16x16x32_bf16 v[82:85], v[176:179], v[204:207], v[82:85]
	v_mfma_f32_16x16x32_bf16 v[70:73], v[168:171], v[212:215], v[70:73]
	v_mfma_f32_16x16x32_bf16 v[66:69], v[176:179], v[212:215], v[66:69]
	s_barrier
	s_mov_b32 m0, s38
	s_add_u32 s12, s12, 0x200080
	s_addc_u32 s13, s13, 0
	ds_read_b128 v[180:183], v141 offset:49152
	ds_read_b128 v[184:187], v141 offset:50176
	ds_read_b128 v[188:191], v141 offset:51200
	ds_read_b128 v[196:199], v141 offset:52224
	ds_read_b128 v[200:203], v141 offset:53248
	ds_read_b128 v[204:207], v141 offset:54272
	ds_read_b128 v[208:211], v141 offset:55296
	ds_read_b128 v[212:215], v141 offset:56320
	s_add_u32 s98, s12, 0xffe00000
	s_addc_u32 s99, s13, -1
	global_load_lds_dwordx4 v130, s[98:99]
	s_mov_b32 m0, s39
	s_nop 0
	global_load_lds_dwordx4 v132, s[98:99]
	s_mov_b32 m0, s40
	s_nop 0
	global_load_lds_dwordx4 v130, s[12:13]
	s_mov_b32 m0, s41
	s_nop 0
	global_load_lds_dwordx4 v132, s[12:13]
	s_mov_b32 m0, s25
	s_nop 0
	s_add_u32 s100, s14, 0xffe00080
	s_addc_u32 s101, s15, -1
	global_load_lds_dwordx4 v130, s[100:101]
	s_mov_b32 m0, s26
	s_nop 0
	global_load_lds_dwordx4 v132, s[100:101]
	s_waitcnt vmcnt(8) lgkmcnt(0)
	s_barrier
	v_mfma_f32_16x16x32_bf16 v[62:65], v[144:147], v[180:183], v[62:65]
	v_mfma_f32_16x16x32_bf16 v[58:61], v[152:155], v[180:183], v[58:61]
	v_mfma_f32_16x16x32_bf16 v[46:49], v[144:147], v[188:191], v[46:49]
	v_mfma_f32_16x16x32_bf16 v[42:45], v[152:155], v[188:191], v[42:45]
	v_mfma_f32_16x16x32_bf16 v[30:33], v[144:147], v[200:203], v[30:33]
	v_mfma_f32_16x16x32_bf16 v[26:29], v[152:155], v[200:203], v[26:29]
	v_mfma_f32_16x16x32_bf16 v[14:17], v[144:147], v[208:211], v[14:17]
	v_mfma_f32_16x16x32_bf16 v[10:13], v[152:155], v[208:211], v[10:13]
	v_mfma_f32_16x16x32_bf16 v[62:65], v[148:151], v[184:187], v[62:65]
	v_mfma_f32_16x16x32_bf16 v[58:61], v[156:159], v[184:187], v[58:61]
	v_mfma_f32_16x16x32_bf16 v[46:49], v[148:151], v[196:199], v[46:49]
	v_mfma_f32_16x16x32_bf16 v[42:45], v[156:159], v[196:199], v[42:45]
	v_mfma_f32_16x16x32_bf16 v[30:33], v[148:151], v[204:207], v[30:33]
	v_mfma_f32_16x16x32_bf16 v[26:29], v[156:159], v[204:207], v[26:29]
	v_mfma_f32_16x16x32_bf16 v[14:17], v[148:151], v[212:215], v[14:17]
	v_mfma_f32_16x16x32_bf16 v[10:13], v[156:159], v[212:215], v[10:13]
	v_mfma_f32_16x16x32_bf16 v[54:57], v[164:167], v[180:183], v[54:57]
	v_mfma_f32_16x16x32_bf16 v[50:53], v[172:175], v[180:183], v[50:53]
	v_mfma_f32_16x16x32_bf16 v[38:41], v[164:167], v[188:191], v[38:41]
	v_mfma_f32_16x16x32_bf16 v[34:37], v[172:175], v[188:191], v[34:37]
	v_mfma_f32_16x16x32_bf16 v[22:25], v[164:167], v[200:203], v[22:25]
	v_mfma_f32_16x16x32_bf16 v[18:21], v[172:175], v[200:203], v[18:21]
	v_mfma_f32_16x16x32_bf16 v[6:9], v[164:167], v[208:211], v[6:9]
	v_mfma_f32_16x16x32_bf16 v[2:5], v[172:175], v[208:211], v[2:5]
	v_mfma_f32_16x16x32_bf16 v[54:57], v[168:171], v[184:187], v[54:57]
	v_mfma_f32_16x16x32_bf16 v[50:53], v[176:179], v[184:187], v[50:53]
	v_mfma_f32_16x16x32_bf16 v[38:41], v[168:171], v[196:199], v[38:41]
	v_mfma_f32_16x16x32_bf16 v[34:37], v[176:179], v[196:199], v[34:37]
	v_mfma_f32_16x16x32_bf16 v[22:25], v[168:171], v[204:207], v[22:25]
	v_mfma_f32_16x16x32_bf16 v[18:21], v[176:179], v[204:207], v[18:21]
	v_mfma_f32_16x16x32_bf16 v[6:9], v[168:171], v[212:215], v[6:9]
	v_mfma_f32_16x16x32_bf16 v[2:5], v[176:179], v[212:215], v[2:5]
	s_barrier
	s_add_i32 s29, s29, 2
	s_add_u32 s10, s10, 0x100
	s_addc_u32 s11, s11, 0
	s_cmpk_lt_u32 s29, 0x7e
	s_cbranch_scc1 .LBB0_1031
	s_waitcnt vmcnt(0)
	s_cmpk_gt_u32 s19, 0xff
	s_cbranch_scc1 .LBB0_1034
	s_barrier
